# phase 0: the 192 modulation items run on workgroups 320..511 instead of 0..191, away from the workgroups that build the small tables
# speedup vs baseline: 1.0115x; 1.0022x over previous
.LBB0_17:
	s_or_b64 exec, exec, s[2:3]
	s_load_dwordx16 s[40:55], s[0:1], 0x0
	s_add_u32 s2, s94, 0x4000
	v_mov_b32_e32 v20, v138
	s_addc_u32 s3, s95, 0
	v_writelane_b32 v207, s2, 2
	s_sub_i32 s36, s96, 0x140
	s_cmpk_gt_u32 s36, 0xbf
	v_lshlrev_b32_e32 v21, 2, v20
	v_writelane_b32 v207, s3, 3
	s_cbranch_scc1 .LBB0_27
	v_and_b32_e32 v1, 31, v20
	v_ashrrev_i32_e32 v0, 5, v20
	s_movk_i32 s2, 0x180
	s_load_dword s13, s[0:1], 0x98
	v_lshlrev_b32_e32 v2, 7, v0
	v_mul_lo_u32 v3, v0, s2
	v_lshlrev_b32_e32 v4, 2, v1
	s_movk_i32 s2, 0x60
	s_movk_i32 s16, 0x3000
	v_or_b32_e32 v10, v3, v4
	v_cmp_gt_i32_e64 s[6:7], s2, v20
	v_or_b32_e32 v6, v2, v4
	v_mad_i64_i32 v[2:3], s[2:3], v2, s16, 0
	s_movk_i32 s12, 0xc00
	v_or_b32_e32 v2, v2, v4
	v_cmp_gt_i32_e64 s[4:5], s12, v20
	s_waitcnt lgkmcnt(0)
	v_lshl_add_u64 v[2:3], s[48:49], 0, v[2:3]
	v_lshlrev_b32_e32 v11, 9, v0
	s_movk_i32 s17, 0x400
	s_movk_i32 s18, 0x800
	v_mov_b32_e32 v5, 0
	s_movk_i32 s19, 0xaff
	s_movk_i32 s20, 0x6000
	s_mov_b32 s21, 0x9000
	s_mov_b32 s22, 0xc000
	s_mov_b32 s23, 0xf000
	s_mov_b32 s24, 0x12000
	s_mov_b32 s25, 0x15000
	s_mov_b32 s26, 0x18000
	s_mov_b32 s27, 0x1b000
	s_mov_b32 s28, 0x1e000
	s_mov_b32 s29, 0x21000
	s_mov_b32 s30, 0x24000
	s_mov_b32 s31, 0x27000
	s_mov_b32 s34, 0x2a000
	s_mov_b32 s35, 0x2d000
	v_add_u32_e32 v12, 0x3000, v10
	v_add_u32_e32 v13, 0x3000, v6
	v_add_u32_e32 v14, 0x3200, v6
	v_add_u32_e32 v15, 0x3400, v6
	v_add_u32_e32 v16, 0x3800, v6
	s_branch .LBB0_20
